# MoBA tile loop: L2-warming dummy loads two K/V tiles ahead (re-test with paired timing)
# baseline (speedup 1.0000x reference)
; #define LAS __attribute__((address_space(3)))
; #define ATT_LOAD(kp0_) do { _Pragma("unroll") for (int _i = 0; _i < 2; ++_i) { const int _grow = rowbase + ((kp0_) + srow + 32 * _i) * rowstride; \
;         kr[_i] = *(const u32x4*)(Kp + (size_t)_grow * ld + sch * 8); vr[_i] = *(const u32x4*)(Vp + (size_t)_grow * ld + sch * 8); } } while (0)
; template <int MODE> ...
;     ...
;         if (it + 1 < ntiles) ATT_LOAD(ATT_KP0(it + 1));
;         LAS unsigned char* const tb = lds + bcur * BUFB;
;         if (hiw && pend) { ATT_PV(lds + bprev * BUFB); pend = false; }
.LBB0_910:
	v_add_u32_e32 v14, s80, v165
	v_add_u32_e32 v10, 64, v14
	v_mad_i64_i32 v[8:9], s[4:5], v10, s94, v[160:161]
	v_mad_i64_i32 v[12:13], s[4:5], v10, s94, v[158:159]
	v_add_u32_e32 v14, 0x60, v14
	global_load_dwordx4 v[8:11], v[8:9], off
	s_nop 0
	global_load_dwordx4 v[16:19], v[12:13], off
	v_mad_i64_i32 v[12:13], s[4:5], v14, s94, v[160:161]
	v_mad_i64_i32 v[20:21], s[4:5], v14, s94, v[158:159]
	global_load_dwordx4 v[12:15], v[12:13], off
	s_nop 0
	global_load_dwordx4 v[20:23], v[20:21], off
	v_add_u32_e32 v230, s80, v165
	v_add_u32_e32 v230, 192, v230
	v_mad_i64_i32 v[232:233], s[4:5], v230, s94, v[160:161]
	global_load_dword v231, v[232:233], off
	v_mad_i64_i32 v[232:233], s[4:5], v230, s94, v[158:159]
	global_load_dword v231, v[232:233], off
	v_add_u32_e32 v230, 32, v230
	v_mad_i64_i32 v[232:233], s[4:5], v230, s94, v[160:161]
	global_load_dword v231, v[232:233], off
	v_mad_i64_i32 v[232:233], s[4:5], v230, s94, v[158:159]
	global_load_dword v231, v[232:233], off
	s_and_b64 s[4:5], s[56:57], s[68:69]
	s_andn2_b64 vcc, exec, s[4:5]
	s_mov_b32 s58, s2
	s_cbranch_vccnz .LBB0_912
	s_mul_i32 s2, s3, 0x9000
	v_add_u32_e32 v162, s2, v196
	ds_read_b64_tr_b16 v[134:135], v162 offset:23040
	ds_read_b64_tr_b16 v[132:133], v162 offset:18432
	ds_read_b64_tr_b16 v[136:137], v162 offset:18464
	ds_read_b64_tr_b16 v[140:141], v162 offset:18496
	ds_read_b64_tr_b16 v[144:145], v162 offset:18528
	ds_read_b64_tr_b16 v[138:139], v162 offset:23072
	ds_read_b64_tr_b16 v[142:143], v162 offset:23104
	ds_read_b64_tr_b16 v[146:147], v162 offset:23136
	s_waitcnt lgkmcnt(6)
	v_mfma_f32_16x16x32_bf16 v[80:83], v[132:135], v[120:123], v[80:83]
	v_mfma_f32_16x16x32_bf16 v[48:51], v[132:135], v[128:131], v[48:51]
	ds_read_b64_tr_b16 v[132:133], v162 offset:18560
	ds_read_b64_tr_b16 v[134:135], v162 offset:23168
	s_waitcnt lgkmcnt(4)
	v_mfma_f32_16x16x32_bf16 v[76:79], v[136:139], v[120:123], v[76:79]
	v_mfma_f32_16x16x32_bf16 v[44:47], v[136:139], v[128:131], v[44:47]
	s_waitcnt lgkmcnt(3)
	v_mfma_f32_16x16x32_bf16 v[72:75], v[140:143], v[120:123], v[72:75]
	v_mfma_f32_16x16x32_bf16 v[40:43], v[140:143], v[128:131], v[40:43]
	s_waitcnt lgkmcnt(2)
	v_mfma_f32_16x16x32_bf16 v[68:71], v[144:147], v[120:123], v[68:71]
	v_mfma_f32_16x16x32_bf16 v[36:39], v[144:147], v[128:131], v[36:39]
	ds_read_b64_tr_b16 v[136:137], v162 offset:18592
	ds_read_b64_tr_b16 v[140:141], v162 offset:18624
	ds_read_b64_tr_b16 v[144:145], v162 offset:18656
	ds_read_b64_tr_b16 v[138:139], v162 offset:23200
	ds_read_b64_tr_b16 v[142:143], v162 offset:23232
	ds_read_b64_tr_b16 v[146:147], v162 offset:23264
	s_waitcnt lgkmcnt(6)
	v_mfma_f32_16x16x32_bf16 v[64:67], v[132:135], v[120:123], v[64:67]
	v_mfma_f32_16x16x32_bf16 v[32:35], v[132:135], v[128:131], v[32:35]
	s_waitcnt lgkmcnt(2)
	v_mfma_f32_16x16x32_bf16 v[60:63], v[136:139], v[120:123], v[60:63]
	v_mfma_f32_16x16x32_bf16 v[28:31], v[136:139], v[128:131], v[28:31]
	s_waitcnt lgkmcnt(1)
	v_mfma_f32_16x16x32_bf16 v[56:59], v[140:143], v[120:123], v[56:59]
	v_mfma_f32_16x16x32_bf16 v[24:27], v[140:143], v[128:131], v[24:27]
	s_waitcnt lgkmcnt(0)
	v_mfma_f32_16x16x32_bf16 v[52:55], v[144:147], v[120:123], v[52:55]
	v_mfma_f32_16x16x32_bf16 v[2:5], v[144:147], v[128:131], v[2:5]
	ds_read_b64_tr_b16 v[134:135], v162 offset:32256
	ds_read_b64_tr_b16 v[132:133], v162 offset:27648
	ds_read_b64_tr_b16 v[136:137], v162 offset:27680
	ds_read_b64_tr_b16 v[140:141], v162 offset:27712
	ds_read_b64_tr_b16 v[144:145], v162 offset:27744
	ds_read_b64_tr_b16 v[138:139], v162 offset:32288
	ds_read_b64_tr_b16 v[142:143], v162 offset:32320
	ds_read_b64_tr_b16 v[146:147], v162 offset:32352
	s_waitcnt lgkmcnt(6)
	v_mfma_f32_16x16x32_bf16 v[80:83], v[132:135], v[100:103], v[80:83]
	s_mov_b64 s[68:69], 0
	v_mfma_f32_16x16x32_bf16 v[48:51], v[132:135], v[124:127], v[48:51]
	ds_read_b64_tr_b16 v[132:133], v162 offset:27776
	ds_read_b64_tr_b16 v[134:135], v162 offset:32384
	s_waitcnt lgkmcnt(4)
	v_mfma_f32_16x16x32_bf16 v[76:79], v[136:139], v[100:103], v[76:79]
	v_mfma_f32_16x16x32_bf16 v[44:47], v[136:139], v[124:127], v[44:47]
	s_waitcnt lgkmcnt(3)
	v_mfma_f32_16x16x32_bf16 v[72:75], v[140:143], v[100:103], v[72:75]
	v_mfma_f32_16x16x32_bf16 v[40:43], v[140:143], v[124:127], v[40:43]
	s_waitcnt lgkmcnt(2)
	v_mfma_f32_16x16x32_bf16 v[68:71], v[144:147], v[100:103], v[68:71]
	v_mfma_f32_16x16x32_bf16 v[36:39], v[144:147], v[124:127], v[36:39]
	ds_read_b64_tr_b16 v[136:137], v162 offset:27808
	ds_read_b64_tr_b16 v[140:141], v162 offset:27840
	ds_read_b64_tr_b16 v[144:145], v162 offset:27872
	ds_read_b64_tr_b16 v[138:139], v162 offset:32416
	ds_read_b64_tr_b16 v[142:143], v162 offset:32448
	ds_read_b64_tr_b16 v[146:147], v162 offset:32480
	s_waitcnt lgkmcnt(6)
	v_mfma_f32_16x16x32_bf16 v[64:67], v[132:135], v[100:103], v[64:67]
	v_mfma_f32_16x16x32_bf16 v[32:35], v[132:135], v[124:127], v[32:35]
	s_waitcnt lgkmcnt(2)
	v_mfma_f32_16x16x32_bf16 v[60:63], v[136:139], v[100:103], v[60:63]
	v_mfma_f32_16x16x32_bf16 v[28:31], v[136:139], v[124:127], v[28:31]
	s_waitcnt lgkmcnt(1)
	v_mfma_f32_16x16x32_bf16 v[56:59], v[140:143], v[100:103], v[56:59]
	v_mfma_f32_16x16x32_bf16 v[24:27], v[140:143], v[124:127], v[24:27]
	s_waitcnt lgkmcnt(0)
	v_mfma_f32_16x16x32_bf16 v[52:55], v[144:147], v[100:103], v[52:55]
	v_mfma_f32_16x16x32_bf16 v[2:5], v[144:147], v[124:127], v[2:5]

; #define LAS __attribute__((address_space(3)))
; #define MFMA16(a, b, c) __builtin_amdgcn_mfma_f32_16x16x32_bf16((a), (b), (c), 0, 0, 0)
; template <int MODE> ...
;     ...
;             const LAS unsigned char* kb = tb + KOFF + c15 * ROWB + g * 16;
; #pragma unroll
;             for (int ks = 0; ks < 4; ++ks) {
; #pragma unroll
;                 for (int kt = 0; kt < 4; ++kt) { const bf16x8 kf = *(const LAS bf16x8*)(kb + kt * 16 * ROWB + ks * 64);
; #pragma unroll
;                     for (int qt = 0; qt < 2; ++qt) s[qt][kt] = MFMA16(kf, qf[qt][ks], s[qt][kt]); }
;             }
; #pragma unroll
;             for (int qt = 0; qt < 2; ++qt) {
;                 const int qp = qw0 + 16 * qt + c15;
;     ...
;                             for (int j = 0; j < 4; ++j) { const int kp = kp0 + 16 * kt + 4 * g + j; bool valid;
;                                 if constexpr (MODE == DIL) valid = (kp <= qp) && (qp - kp <= 128);
;                                 else valid = own ? (kp <= qp) : (((selq[qt] >> bjk) & 1u) != 0u);
.LBB0_915:
	v_add3_u32 v197, s59, v193, v0
	ds_read_b128 v[100:103], v197
	ds_read_b128 v[200:203], v197 offset:64
	ds_read_b128 v[124:127], v197 offset:4608
	ds_read_b128 v[132:135], v197 offset:9216
	ds_read_b128 v[140:143], v197 offset:13824
	s_add_i32 s2, s80, 63
	s_cmp_gt_i32 s2, s38
	s_cselect_b64 s[2:3], -1, 0
	s_xor_b64 s[4:5], s[70:71], -1
	s_waitcnt vmcnt(15) lgkmcnt(4)
	v_mfma_f32_16x16x32_bf16 v[120:123], v[100:103], v[112:115], 0
	s_and_b64 s[72:73], s[4:5], s[2:3]
	s_mov_b64 s[74:75], -1
	s_waitcnt vmcnt(11)
	v_mfma_f32_16x16x32_bf16 v[100:103], v[100:103], v[116:119], 0
	s_waitcnt lgkmcnt(3)
	v_mfma_f32_16x16x32_bf16 v[120:123], v[200:203], v[104:107], v[120:123]
	s_waitcnt vmcnt(10)
	v_mfma_f32_16x16x32_bf16 v[100:103], v[200:203], v[108:111], v[100:103]
	ds_read_b128 v[200:203], v197 offset:4672
	s_waitcnt lgkmcnt(3)
	v_mfma_f32_16x16x32_bf16 v[128:131], v[124:127], v[112:115], 0
	v_mfma_f32_16x16x32_bf16 v[124:127], v[124:127], v[116:119], 0
	s_waitcnt lgkmcnt(0)
	v_mfma_f32_16x16x32_bf16 v[128:131], v[200:203], v[104:107], v[128:131]
	v_mfma_f32_16x16x32_bf16 v[124:127], v[200:203], v[108:111], v[124:127]
	ds_read_b128 v[200:203], v197 offset:9280
	v_mfma_f32_16x16x32_bf16 v[136:139], v[132:135], v[112:115], 0
	v_mfma_f32_16x16x32_bf16 v[132:135], v[132:135], v[116:119], 0
	s_waitcnt lgkmcnt(0)
	v_mfma_f32_16x16x32_bf16 v[136:139], v[200:203], v[104:107], v[136:139]
	v_mfma_f32_16x16x32_bf16 v[132:135], v[200:203], v[108:111], v[132:135]
	ds_read_b128 v[200:203], v197 offset:13888
	v_mfma_f32_16x16x32_bf16 v[144:147], v[140:143], v[112:115], 0
	v_mfma_f32_16x16x32_bf16 v[140:143], v[140:143], v[116:119], 0
	s_waitcnt lgkmcnt(0)
	v_mfma_f32_16x16x32_bf16 v[144:147], v[200:203], v[104:107], v[144:147]
	v_mfma_f32_16x16x32_bf16 v[140:143], v[200:203], v[108:111], v[140:143]
	ds_read_b128 v[200:203], v197 offset:128
	s_waitcnt lgkmcnt(0)
	v_mfma_f32_16x16x32_bf16 v[120:123], v[200:203], v[92:95], v[120:123]
	s_waitcnt vmcnt(9)
	v_mfma_f32_16x16x32_bf16 v[100:103], v[200:203], v[96:99], v[100:103]
	ds_read_b128 v[200:203], v197 offset:4736
	s_waitcnt lgkmcnt(0)
	v_mfma_f32_16x16x32_bf16 v[128:131], v[200:203], v[92:95], v[128:131]
	v_mfma_f32_16x16x32_bf16 v[124:127], v[200:203], v[96:99], v[124:127]
	ds_read_b128 v[200:203], v197 offset:9344
	s_waitcnt lgkmcnt(0)
	v_mfma_f32_16x16x32_bf16 v[204:207], v[200:203], v[92:95], v[136:139]
	s_nop 2
	ds_read_b128 v[136:139], v197 offset:13952
	v_mfma_f32_16x16x32_bf16 v[132:135], v[200:203], v[96:99], v[132:135]
	s_waitcnt lgkmcnt(0)
	v_mfma_f32_16x16x32_bf16 v[200:203], v[136:139], v[92:95], v[144:147]
	v_mfma_f32_16x16x32_bf16 v[208:211], v[136:139], v[96:99], v[140:143]
	ds_read_b128 v[136:139], v197 offset:192
	s_waitcnt lgkmcnt(0)
	v_mfma_f32_16x16x32_bf16 v[144:147], v[136:139], v[88:91], v[120:123]
	s_nop 2
	ds_read_b128 v[120:123], v197 offset:4800
	s_waitcnt vmcnt(8)
	v_mfma_f32_16x16x32_bf16 v[136:139], v[136:139], v[84:87], v[100:103]
	s_waitcnt lgkmcnt(0)
	v_mfma_f32_16x16x32_bf16 v[100:103], v[120:123], v[88:91], v[128:131]
	s_nop 2
	ds_read_b128 v[128:131], v197 offset:14016
	v_mfma_f32_16x16x32_bf16 v[124:127], v[120:123], v[84:87], v[124:127]
	ds_read_b128 v[120:123], v197 offset:9408
	v_xor_b32_e32 v197, 16, v184
	s_waitcnt lgkmcnt(0)
	v_mfma_f32_16x16x32_bf16 v[140:143], v[120:123], v[88:91], v[204:207]
	v_mfma_f32_16x16x32_bf16 v[132:135], v[120:123], v[84:87], v[132:135]
	v_mfma_f32_16x16x32_bf16 v[120:123], v[128:131], v[88:91], v[200:203]
	s_nop 2
	v_and_b32_e32 v200, 64, v184
	v_add_u32_e32 v201, 64, v200
	v_cmp_lt_i32_e32 vcc, v197, v201
	v_mfma_f32_16x16x32_bf16 v[128:131], v[128:131], v[84:87], v[208:211]
	v_add_u32_e32 v203, s80, v153
	v_cndmask_b32_e32 v197, v184, v197, vcc
	v_lshlrev_b32_e32 v200, 2, v197
	v_xor_b32_e32 v197, 32, v184
	v_cmp_lt_i32_e32 vcc, v197, v201
	v_add_u32_e32 v212, 2, v203
	v_add_u32_e32 v210, 3, v203
	v_cndmask_b32_e32 v197, v184, v197, vcc
	v_add_u32_e32 v211, 16, v203
	v_add_u32_e32 v209, 17, v203
	v_add_u32_e32 v207, 18, v203
	v_add_u32_e32 v208, 19, v203
	v_add_u32_e32 v206, 32, v203
	v_add_u32_e32 v204, 33, v203
	v_add_u32_e32 v205, 34, v203
	v_add_u32_e32 v202, 35, v203
	v_lshlrev_b32_e32 v201, 2, v197
	s_and_b64 vcc, exec, s[72:73]
	v_cmp_le_i32_e64 s[2:3], v203, v189
	v_cmp_lt_i32_e64 s[4:5], v203, v189
	v_cmp_le_i32_e64 s[10:11], v212, v189
	v_cmp_le_i32_e64 s[24:25], v210, v189
	v_cmp_le_i32_e64 s[16:17], v211, v189
	v_cmp_le_i32_e64 s[12:13], v209, v189
	v_cmp_le_i32_e64 s[20:21], v207, v189
	v_cmp_le_i32_e64 s[18:19], v208, v189
	v_cmp_le_i32_e64 s[6:7], v206, v189
	v_cmp_le_i32_e64 s[22:23], v204, v189
	v_cmp_le_i32_e64 s[14:15], v205, v189
	v_cmp_le_i32_e64 s[8:9], v202, v189
	s_cbranch_vccz .LBB0_917
; template <int MODE> ...
;     ...
;                             for (int j = 0; j < 4; ++j) { const int kp = kp0 + 16 * kt + 4 * g + j; bool valid;
;                                 if constexpr (MODE == DIL) valid = (kp <= qp) && (qp - kp <= 128);
;                                 else valid = own ? (kp <= qp) : (((selq[qt] >> bjk) & 1u) != 0u);
;                                 p[kt][j] = valid ? s[qt][kt][j] * SCL2 : -1e30f; mx = fmaxf(mx, p[kt][j]); }
;                         mx = fmaxf(mx, __shfl_xor(mx, 16)); mx = fmaxf(mx, __shfl_xor(mx, 32));
;                         mnew = fmaxf(mrun[qt], mx); alpha = __builtin_amdgcn_exp2f(mrun[qt] - mnew); mrun[qt] = mnew;
; #pragma unroll
;                         for (int kt = 0; kt < 4; ++kt)
; #pragma unroll
;                             for (int j = 0; j < 4; ++j) { p[kt][j] = __builtin_amdgcn_exp2f(p[kt][j] - mnew); rs += p[kt][j]; }
;                     }
;                     rs += __shfl_xor(rs, 16); rs += __shfl_xor(rs, 32);
;                     lrun[qt] = lrun[qt] * alpha + rs;
	v_mul_f32_e32 v197, 0x3e0293ee, v144
	v_cndmask_b32_e64 v213, v187, v197, s[2:3]
	v_mul_f32_e32 v197, 0x3e0293ee, v145
	v_add_u32_e32 v225, 48, v203
	v_cndmask_b32_e64 v214, v187, v197, s[4:5]
	v_mul_f32_e32 v215, 0x3e0293ee, v146
	v_mul_f32_e32 v216, 0x3e0293ee, v147
	v_mul_f32_e32 v226, 0x3e0293ee, v120
	v_cmp_le_i32_e32 vcc, v225, v189
	v_max3_f32 v197, v213, s33, v214
	v_cndmask_b32_e64 v215, v187, v215, s[10:11]
	v_cndmask_b32_e64 v216, v187, v216, s[24:25]
	v_mul_f32_e32 v217, 0x3e0293ee, v100
	v_mul_f32_e32 v218, 0x3e0293ee, v101
	v_cndmask_b32_e32 v225, v187, v226, vcc
	v_add_u32_e32 v226, 49, v203
	v_max3_f32 v197, v197, v215, v216
	v_cndmask_b32_e64 v217, v187, v217, s[16:17]
	v_cndmask_b32_e64 v218, v187, v218, s[12:13]
	v_mul_f32_e32 v219, 0x3e0293ee, v102
	v_mul_f32_e32 v220, 0x3e0293ee, v103
	v_mul_f32_e32 v227, 0x3e0293ee, v121
	v_cmp_le_i32_e32 vcc, v226, v189
	v_max3_f32 v197, v197, v217, v218
	v_cndmask_b32_e64 v219, v187, v219, s[20:21]
	v_cndmask_b32_e64 v220, v187, v220, s[18:19]
	v_mul_f32_e32 v221, 0x3e0293ee, v140
	v_mul_f32_e32 v222, 0x3e0293ee, v141
	v_cndmask_b32_e32 v226, v187, v227, vcc
	v_add_u32_e32 v227, 50, v203
	v_max3_f32 v197, v197, v219, v220
	v_cndmask_b32_e64 v221, v187, v221, s[6:7]
	v_cndmask_b32_e64 v222, v187, v222, s[22:23]
	v_mul_f32_e32 v223, 0x3e0293ee, v142
	v_mul_f32_e32 v224, 0x3e0293ee, v143
	v_mul_f32_e32 v228, 0x3e0293ee, v122
	v_cmp_le_i32_e32 vcc, v227, v189
	v_max3_f32 v197, v197, v221, v222
	v_cndmask_b32_e64 v223, v187, v223, s[14:15]
	v_cndmask_b32_e64 v224, v187, v224, s[8:9]
	v_cndmask_b32_e32 v227, v187, v228, vcc
	v_add_u32_e32 v228, 51, v203
	v_max3_f32 v197, v197, v223, v224
	v_mul_f32_e32 v229, 0x3e0293ee, v123
	v_cmp_le_i32_e32 vcc, v228, v189
	v_max3_f32 v197, v197, v225, v226
	s_mov_b64 s[74:75], 0
	v_cndmask_b32_e32 v228, v187, v229, vcc
	v_max3_f32 v197, v197, v227, v228
	ds_bpermute_b32 v229, v200, v197
	s_waitcnt lgkmcnt(0)
	v_max_f32_e32 v229, v229, v229
	v_max_f32_e32 v197, v197, v229
	ds_bpermute_b32 v229, v201, v197
	s_waitcnt lgkmcnt(0)
	v_max3_f32 v197, v199, v197, v229
	v_sub_f32_e32 v213, v213, v197
	v_exp_f32_e32 v213, v213
	v_sub_f32_e32 v214, v214, v197
	v_exp_f32_e32 v214, v214
	v_sub_f32_e32 v215, v215, v197
	v_exp_f32_e32 v215, v215
	v_sub_f32_e32 v216, v216, v197
	v_exp_f32_e32 v216, v216
	v_sub_f32_e32 v217, v217, v197
	v_add_f32_e32 v229, 0, v213
	v_exp_f32_e32 v217, v217
	v_sub_f32_e32 v218, v218, v197
	v_add_f32_e32 v229, v214, v229
	v_exp_f32_e32 v218, v218
	v_sub_f32_e32 v219, v219, v197
	v_add_f32_e32 v229, v215, v229
	v_exp_f32_e32 v219, v219
	v_sub_f32_e32 v220, v220, v197
	v_add_f32_e32 v229, v216, v229
	v_exp_f32_e32 v220, v220
	v_sub_f32_e32 v221, v221, v197
	v_add_f32_e32 v229, v217, v229
	v_exp_f32_e32 v221, v221
	v_sub_f32_e32 v222, v222, v197
	v_add_f32_e32 v229, v218, v229
	v_exp_f32_e32 v222, v222
	v_sub_f32_e32 v223, v223, v197
	v_add_f32_e32 v229, v219, v229
	v_exp_f32_e32 v223, v223
	v_sub_f32_e32 v224, v224, v197
	v_add_f32_e32 v229, v220, v229
	v_exp_f32_e32 v224, v224
	v_sub_f32_e32 v225, v225, v197
	v_add_f32_e32 v229, v221, v229
	v_exp_f32_e32 v225, v225
	v_sub_f32_e32 v226, v226, v197
	v_add_f32_e32 v229, v222, v229
	v_exp_f32_e32 v226, v226
	v_sub_f32_e32 v227, v227, v197
	v_add_f32_e32 v229, v223, v229
	v_exp_f32_e32 v227, v227
	v_add_f32_e32 v229, v224, v229
	v_add_f32_e32 v229, v225, v229
	v_add_f32_e32 v229, v226, v229
	v_add_f32_e32 v229, v227, v229
	v_sub_f32_e32 v228, v228, v197

; #define LAS __attribute__((address_space(3)))
; template <int MODE> ...
;     ...
;         if (it + 1 < ntiles) {
;             LAS unsigned char* const nb = lds + (bcur == 2 ? 0 : bcur + 1) * BUFB;
; #pragma unroll
;             for (int i = 0; i < 2; ++i) { *(LAS u32x4*)(nb + KOFF + (srow + 32 * i) * ROWB + sch * 16) = kr[i]; *(LAS u32x4*)(nb + VOFF + (srow + 32 * i) * ROWB + sch * 16) = vr[i]; }
;         }
;         if constexpr (MODE == SB) { if (lane == 0) ((LAS unsigned*)(lds + DONE_OFF + (it & 1) * 32))[wid] = __any((Rrun[0] != 0.f) || (Rrun[1] != 0.f)) ? 0u : 1u; }
;         __syncthreads();
;         bprev = bcur; bcur = bcur == 2 ? 0 : bcur + 1;
.LBB0_934:
	s_add_i32 s35, s35, 0x9000
	s_add_i32 s2, s58, 1
	s_cmp_eq_u32 s58, 2
	s_cselect_b32 s3, 0, s35
	s_cselect_b32 s2, 0, s2
	s_add_i32 s80, s80, 64
	v_add_u32_e32 v132, s3, v194
	s_cmp_eq_u32 s37, s80
	s_waitcnt vmcnt(7)
	ds_write_b128 v132, v[8:11]
	s_waitcnt vmcnt(6)
	ds_write_b128 v132, v[16:19] offset:18432
	s_waitcnt vmcnt(5)
	ds_write_b128 v132, v[12:15] offset:9216
	s_waitcnt vmcnt(4)
	ds_write_b128 v132, v[20:23] offset:27648
	s_waitcnt lgkmcnt(0)
	s_barrier
	s_cbranch_scc1 .LBB0_936
	v_mov_b32_e32 v198, v141
	v_mov_b32_e32 v199, v197
	s_mov_b32 s3, s58
	s_branch .LBB0_910
